# PB attention inner loop (live copy): ALiBi reassociated (pk adds + per-lane base folded into max reference), QK MFMAs spread through softmax with 2 accumulators, exps in place interleaved, V/K fragmen
# baseline (speedup 1.0000x reference)
; #define LAS __attribute__((address_space(3)))
; __device__ __forceinline__ void attn_unit(LAS unsigned char* lds, const bf16* PROJ, bf16* DA, const float* sinkl, int unit, int tid, int wid, int lane) {
;     ...
; #pragma unroll
;         for (int i = 0; i < 3; ++i) {
;             const int idx = tid + 512 * (3 * hp + i), c = idx >> 3, ch = idx & 7;
;             *(LAS v4u*)(Ks + c * KS_PITCH + ch * 8) = kreg[i];
;             LAS bf16* vp = Vt + (ch * 8) * VT_PITCH + c;
;             vp[0 * VT_PITCH] = (bf16)(vreg[i].x & 0xffffu); vp[1 * VT_PITCH] = (bf16)(vreg[i].x >> 16);
;             vp[2 * VT_PITCH] = (bf16)(vreg[i].y & 0xffffu); vp[3 * VT_PITCH] = (bf16)(vreg[i].y >> 16);
;             vp[4 * VT_PITCH] = (bf16)(vreg[i].z & 0xffffu); vp[5 * VT_PITCH] = (bf16)(vreg[i].z >> 16);
;             vp[6 * VT_PITCH] = (bf16)(vreg[i].w & 0xffffu); vp[7 * VT_PITCH] = (bf16)(vreg[i].w >> 16);
;         }
;     }
;     __syncthreads();
;     const int r32 = lane & 31, hi = lane >> 5;
;     const int hq = hk * 4 + (wid >> 1);
;     const float slope2 = __builtin_amdgcn_exp2f(-(float)(hq + 1)) * LOG2E;
;     const float sink2 = sinkl[hq] * LOG2E;
;     const float NEG = -INFINITY;
;     const bool edge_n = (n == 0) || (n == 31);
; #pragma unroll 1
;     for (int sb = 0; sb < 2; ++sb) {
;         const int a0 = 64 * (wid & 1) + 32 * sb, a = a0 + r32;
;         const size_t qrow = rowb + (size_t)n * 128 + a;
;         bf16x8 qf[4];
; #pragma unroll
;         for (int ks = 0; ks < 4; ++ks) qf[ks] = *(const bf16x8*)(PROJ + qrow * INW + 512 + hq * 64 + ks * 16 + hi * 8);
;         float mrun = sink2, l = 0.f;
;         f32x16 o0, o1;
; #pragma unroll
;         for (int r = 0; r < 16; ++r) { o0[r] = 0.f; o1[r] = 0.f; }
;         const float fb0 = (float)(r32 + 128 - 4 * hi);
;         f32x16 pn;
.LBB0_378:
	s_or_b64 exec, exec, s[36:37]
	v_mad_u64_u32 v[30:31], s[26:27], v26, s3, v[40:41]
	s_waitcnt vmcnt(1)
	ds_write_b128 v30, v[6:9]
	v_lshl_add_u32 v6, v26, 1, v41
	s_waitcnt vmcnt(0)
	ds_write_b16 v6, v2 offset:55296
	ds_write_b16_d16_hi v6, v2 offset:56072
	ds_write_b16 v6, v3 offset:56848
	ds_write_b16_d16_hi v6, v3 offset:57624
	ds_write_b16 v6, v4 offset:58400
	ds_write_b16_d16_hi v6, v4 offset:59176
	ds_write_b16 v6, v5 offset:59952
	ds_write_b16_d16_hi v6, v5 offset:60728
	v_mad_u64_u32 v[2:3], s[26:27], v27, s3, v[40:41]
	s_lshl_b64 s[24:25], s[70:71], 2
	v_readlane_b32 s13, v239, 11
	ds_write_b128 v2, v[14:17]
	v_lshl_add_u32 v2, v27, 1, v41
	s_add_u32 s24, s13, s24
	v_readlane_b32 s13, v239, 12
	ds_write_b16 v2, v10 offset:55296
	ds_write_b16_d16_hi v2, v10 offset:56072
	ds_write_b16 v2, v11 offset:56848
	ds_write_b16_d16_hi v2, v11 offset:57624
	ds_write_b16 v2, v12 offset:58400
	ds_write_b16_d16_hi v2, v12 offset:59176
	ds_write_b16 v2, v13 offset:59952
	ds_write_b16_d16_hi v2, v13 offset:60728
	v_mad_u64_u32 v[2:3], s[26:27], v28, s3, v[40:41]
	s_addc_u32 s25, s13, s25
	ds_write_b128 v2, v[22:25]
	v_lshl_add_u32 v2, v28, 1, v41
	ds_write_b16 v2, v18 offset:55296
	ds_write_b16_d16_hi v2, v18 offset:56072
	ds_write_b16 v2, v19 offset:56848
	ds_write_b16_d16_hi v2, v19 offset:57624
	ds_write_b16 v2, v20 offset:58400
	ds_write_b16_d16_hi v2, v20 offset:59176
	ds_write_b16 v2, v21 offset:59952
	ds_write_b16_d16_hi v2, v21 offset:60728
	s_waitcnt lgkmcnt(0)
	s_barrier
	global_load_dword v3, v66, s[24:25]
	v_mul_f32_e32 v204, 0x00000000, v162
	v_mul_f32_e32 v205, 0x3f800000, v162
	v_mul_f32_e32 v206, 0x40000000, v162
	v_mul_f32_e32 v207, 0x40400000, v162
	v_mul_f32_e32 v208, 0x41000000, v162
	v_mul_f32_e32 v209, 0x41100000, v162
	v_mul_f32_e32 v210, 0x41200000, v162
	v_mul_f32_e32 v211, 0x41300000, v162
	v_mul_f32_e32 v212, 0x41800000, v162
	v_mul_f32_e32 v213, 0x41880000, v162
	v_mul_f32_e32 v214, 0x41900000, v162
	v_mul_f32_e32 v215, 0x41980000, v162
	v_mul_f32_e32 v216, 0x41c00000, v162
	v_mul_f32_e32 v217, 0x41c80000, v162
	v_mul_f32_e32 v218, 0x41d00000, v162
	v_mul_f32_e32 v219, 0x41d80000, v162
	v_and_b32_e32 v67, 63, v173
	v_bfe_u32 v2, v173, 5, 1
	v_readlane_b32 s24, v238, 7
	v_and_b32_e32 v85, 31, v173
	v_lshlrev_b32_e32 v4, 3, v2
	v_lshlrev_b32_e32 v5, 2, v2
	v_lshlrev_b32_e32 v2, 4, v2
	v_or_b32_e32 v6, 32, v67
	v_readlane_b32 s25, v238, 8
	v_mul_u32_u24_e32 v7, 0x308, v85
	v_mul_u32_u24_e32 v8, 0x308, v6
	v_readlane_b32 s13, v238, 15
	v_add_u32_e32 v84, 0, v2
	v_sub_u32_e32 v95, v85, v5
	v_add3_u32 v96, v8, v4, s13
	v_add3_u32 v97, v7, v4, s13
	v_readlane_b32 s13, v238, 19
	v_add_u32_e32 v99, s80, v6
	s_mov_b32 s36, 0
	v_sub_u32_e32 v98, s13, v5
	s_mov_b64 s[38:39], -1
	s_mov_b32 s23, 0
	s_waitcnt vmcnt(0)
	v_mul_f32_e32 v94, 0x3fb8aa3b, v3
	v_mov_b32_e32 v3, v66
	v_lshl_add_u64 v[86:87], s[24:25], 0, v[2:3]
	v_readlane_b32 s24, v238, 9
	v_readlane_b32 s25, v238, 10
	s_nop 1
	v_lshl_add_u64 v[88:89], s[24:25], 0, v[2:3]
	s_branch .LBB0_380

; #define ATT_QK(dst, cblk) do { _Pragma("unroll") for (int r = 0; r < 16; ++r) dst[r] = 0.f; \
;             _Pragma("unroll") for (int ks = 0; ks < 4; ++ks) { const bf16x8 kf = *(const LAS bf16x8*)(Ks + ((cblk) + r32) * KS_PITCH + ks * 16 + hi * 8); \
;                 dst = __builtin_amdgcn_mfma_f32_32x32x16_bf16(kf, qf[ks], dst, 0, 0, 0); } } while (0)
; __device__ __forceinline__ void attn_unit(LAS unsigned char* lds, const bf16* PROJ, bf16* DA, const float* sinkl, int unit, int tid, int wid, int lane) {
;     ...
;             if (i < 8) ATT_QK(pn, c0 + 32);
;             const float fb = fb0 - (float)(32 * i);
;             const int sb0 = s0 + c0 + 4 * hi;
;             const float kmin = fmaxf(fb - 128.0f, (float)(-sb0)), kmax = fminf(fb + 128.0f, (float)(SEQ - 1 - sb0));
;             const float kmid = 0.5f * (kmin + kmax), khw = 0.5f * (kmax - kmin);
;             float mx = NEG;
; #pragma unroll
;             for (int r = 0; r < 16; ++r) { const float kr = (float)((r & 3) + 8 * (r >> 2)); p[r] = p[r] - slope2 * fabsf(fb - kr); }
;             if ((i == 0) || (i == 8) || edge_n) {
; #pragma unroll
;                 for (int r = 0; r < 16; ++r) { const float kr = (float)((r & 3) + 8 * (r >> 2)); p[r] = (fabsf(kr - kmid) <= khw) ? p[r] : NEG; }
.LBB0_381:
	ds_read_b128 v[174:177], v92
	ds_read_b128 v[178:181], v92 offset:32
	ds_read_b128 v[182:185], v92 offset:64
	ds_read_b128 v[186:189], v92 offset:96
.LBB0_382:
	v_add_u32_e32 v105, s23, v95
	v_add_u32_e32 v104, 0x80, v105
	v_cvt_f32_i32_e32 v104, v104
	s_cmp_eq_u32 s23, 0xffffff80
	s_cbranch_scc1 .Lalibi_mixed
	v_mul_f32_e32 v146, v162, v104
	s_cmp_gt_i32 s23, 0xffffff80
	s_cbranch_scc0 .Lalibi_neg
	v_pk_add_f32 v[50:51], v[50:51], v[204:205]
	v_pk_add_f32 v[52:53], v[52:53], v[206:207]
	v_pk_add_f32 v[54:55], v[54:55], v[208:209]
	v_pk_add_f32 v[56:57], v[56:57], v[210:211]
	v_pk_add_f32 v[58:59], v[58:59], v[212:213]
	v_pk_add_f32 v[60:61], v[60:61], v[214:215]
	v_pk_add_f32 v[62:63], v[62:63], v[216:217]
	v_pk_add_f32 v[64:65], v[64:65], v[218:219]
	s_branch .Lalibi_done
.Lalibi_neg:
	v_pk_add_f32 v[50:51], v[50:51], v[204:205] neg_lo:[0,1] neg_hi:[0,1]
	v_pk_add_f32 v[52:53], v[52:53], v[206:207] neg_lo:[0,1] neg_hi:[0,1]
	v_pk_add_f32 v[54:55], v[54:55], v[208:209] neg_lo:[0,1] neg_hi:[0,1]
	v_pk_add_f32 v[56:57], v[56:57], v[210:211] neg_lo:[0,1] neg_hi:[0,1]
	v_pk_add_f32 v[58:59], v[58:59], v[212:213] neg_lo:[0,1] neg_hi:[0,1]
	v_pk_add_f32 v[60:61], v[60:61], v[214:215] neg_lo:[0,1] neg_hi:[0,1]
	v_pk_add_f32 v[62:63], v[62:63], v[216:217] neg_lo:[0,1] neg_hi:[0,1]
	v_pk_add_f32 v[64:65], v[64:65], v[218:219] neg_lo:[0,1] neg_hi:[0,1]
	v_xor_b32_e32 v146, 0x80000000, v146
	s_branch .Lalibi_done
.Lalibi_mixed:
	v_fma_f32 v50, -v162, |v104|, v50
	v_subrev_f32_e32 v106, 0x3f800000, v104
	v_fma_f32 v51, -v163, |v106|, v51
	v_subrev_f32_e32 v107, 0x40000000, v104
	v_fma_f32 v52, -v162, |v107|, v52
	v_subrev_f32_e32 v106, 0x40400000, v104
	v_fma_f32 v53, -v163, |v106|, v53
	v_subrev_f32_e32 v107, 0x41000000, v104
	v_fma_f32 v54, -v162, |v107|, v54
	v_subrev_f32_e32 v106, 0x41100000, v104
	v_fma_f32 v55, -v163, |v106|, v55
	v_subrev_f32_e32 v107, 0x41200000, v104
	v_fma_f32 v56, -v162, |v107|, v56
	v_subrev_f32_e32 v106, 0x41300000, v104
	v_fma_f32 v57, -v163, |v106|, v57
	v_subrev_f32_e32 v107, 0x41800000, v104
	v_fma_f32 v58, -v162, |v107|, v58
	v_subrev_f32_e32 v106, 0x41880000, v104
	v_fma_f32 v59, -v163, |v106|, v59
	v_subrev_f32_e32 v107, 0x41900000, v104
	v_fma_f32 v60, -v162, |v107|, v60
	v_subrev_f32_e32 v106, 0x41980000, v104
	v_fma_f32 v61, -v163, |v106|, v61
	v_subrev_f32_e32 v107, 0x41c00000, v104
	v_fma_f32 v62, -v162, |v107|, v62
	v_subrev_f32_e32 v106, 0x41c80000, v104
	v_fma_f32 v63, -v163, |v106|, v63
	v_subrev_f32_e32 v107, 0x41d00000, v104
	v_fma_f32 v64, -v162, |v107|, v64
	v_subrev_f32_e32 v106, 0x41d80000, v104
	v_fma_f32 v65, -v163, |v106|, v65
	v_mov_b32_e32 v146, 0
.Lalibi_done:
	s_waitcnt lgkmcnt(3)
	v_mfma_f32_32x32x16_bf16 v[34:49], v[174:177], v[68:71], 0
	s_and_b32 s25, s24, 7
	s_cmp_eq_u32 s25, 0
	s_cbranch_scc1 .LBB0_391
	s_cmp_gt_i32 s78, 30
	s_mov_b64 s[38:39], -1
	s_cbranch_scc1 .LBB0_385
	s_cmp_eq_u32 s78, 0
	s_cselect_b64 s[38:39], -1, 0

; __device__ __forceinline__ unsigned cvt_pk_bf16(float lo, float hi) { f32x2c v = {lo, hi}; bf16x2c b = __builtin_convertvector(v, bf16x2c); return __builtin_bit_cast(unsigned, b); }
; #define LAS __attribute__((address_space(3)))
; __device__ __forceinline__ void attn_unit(LAS unsigned char* lds, const bf16* PROJ, bf16* DA, const float* sinkl, int unit, int tid, int wid, int lane) {
;     ...
;             if (i < 8) ATT_QK(pn, c0 + 32);
;     ...
;             for (int r = 0; r < 16; ++r) mx = fmaxf(mx, p[r]);
;             { const auto rr = __builtin_amdgcn_permlane32_swap(__float_as_uint(mx), __float_as_uint(mx), false, false); mx = fmaxf(__uint_as_float(rr[0]), __uint_as_float(rr[1])); }
;             if (__any(mx > mrun + 8.0f)) {
;                 const float mnew = fmaxf(mrun, mx), alpha = __builtin_amdgcn_exp2f(mrun - mnew);
;                 mrun = mnew; l *= alpha;
; #pragma unroll
;                 for (int r = 0; r < 16; ++r) { o0[r] *= alpha; o1[r] *= alpha; }
;             }
;             float ps = 0.f;
; #pragma unroll
;             for (int r = 0; r < 16; ++r) { p[r] = __builtin_amdgcn_exp2f(p[r] - mrun); ps += p[r]; }
;             l += ps;
; #pragma unroll
;             for (int s = 0; s < 2; ++s) {
;                 v4u pw; pw.x = pg8::cvt_pk_bf16(p[8 * s + 0], p[8 * s + 1]); pw.y = pg8::cvt_pk_bf16(p[8 * s + 2], p[8 * s + 3]);
;                 pw.z = pg8::cvt_pk_bf16(p[8 * s + 4], p[8 * s + 5]); pw.w = pg8::cvt_pk_bf16(p[8 * s + 6], p[8 * s + 7]);
;                 const bf16x8 pb = __builtin_bit_cast(bf16x8, pw);
; #pragma unroll
;                 for (int db = 0; db < 2; ++db) {
;                     const LAS bf16* vp = Vt + (db * 32 + r32) * VT_PITCH + c0 + 16 * s + 4 * hi;
;                     const s16x4 vlo = *(const LAS s16x4*)vp, vhi = *(const LAS s16x4*)(vp + 8);
;                     const bf16x8 vf = (bf16x8){vlo[0], vlo[1], vlo[2], vlo[3], vhi[0], vhi[1], vhi[2], vhi[3]};
;                     if (db == 0) o0 = __builtin_amdgcn_mfma_f32_32x32x16_bf16(vf, pb, o0, 0, 0, 0);
;                     else         o1 = __builtin_amdgcn_mfma_f32_32x32x16_bf16(vf, pb, o1, 0, 0, 0);
;                 }
;             }
.LBB0_387:
	s_waitcnt lgkmcnt(2)
	v_mfma_f32_32x32x16_bf16 v[220:235], v[178:181], v[72:75], 0
	v_max3_f32 v104, v50, s22, v51
	v_max3_f32 v104, v104, v52, v53
	v_max3_f32 v104, v104, v54, v55
	v_max3_f32 v104, v104, v56, v57
	v_max3_f32 v104, v104, v58, v59
	v_max3_f32 v104, v104, v60, v61
	v_max3_f32 v104, v104, v62, v63
	v_max3_f32 v104, v104, v64, v65
	v_mov_b32_e32 v105, v104
	s_nop 1
	v_permlane32_swap_b32_e32 v104, v105
	v_max_f32_e32 v105, v105, v105
	v_max_f32_e32 v104, v104, v104
	v_max_f32_e32 v104, v104, v105
	v_sub_f32_e32 v104, v104, v146
	v_add_f32_e32 v105, 0x41000000, v103
	v_cmp_gt_f32_e32 vcc, v104, v105
	s_cbranch_vccz .LBB0_389
	v_max_f32_e32 v104, v104, v104
	v_max_f32_e32 v105, v103, v103
	v_max_f32_e32 v105, v105, v104
	v_sub_f32_e32 v103, v103, v105
	v_exp_f32_e32 v104, v103
	v_mov_b32_e32 v103, v105
	v_pk_mul_f32 v[32:33], v[32:33], v[104:105] op_sel_hi:[1,0]
	v_pk_mul_f32 v[30:31], v[30:31], v[104:105] op_sel_hi:[1,0]
	v_pk_mul_f32 v[28:29], v[28:29], v[104:105] op_sel_hi:[1,0]
	v_pk_mul_f32 v[26:27], v[26:27], v[104:105] op_sel_hi:[1,0]
	v_pk_mul_f32 v[24:25], v[24:25], v[104:105] op_sel_hi:[1,0]
	v_pk_mul_f32 v[22:23], v[22:23], v[104:105] op_sel_hi:[1,0]
	v_pk_mul_f32 v[20:21], v[20:21], v[104:105] op_sel_hi:[1,0]
	v_pk_mul_f32 v[18:19], v[18:19], v[104:105] op_sel_hi:[1,0]
	v_pk_mul_f32 v[16:17], v[16:17], v[104:105] op_sel_hi:[1,0]
	v_pk_mul_f32 v[14:15], v[14:15], v[104:105] op_sel_hi:[1,0]
	v_pk_mul_f32 v[12:13], v[12:13], v[104:105] op_sel_hi:[1,0]
	v_pk_mul_f32 v[10:11], v[10:11], v[104:105] op_sel_hi:[1,0]
	v_pk_mul_f32 v[8:9], v[8:9], v[104:105] op_sel_hi:[1,0]
	v_pk_mul_f32 v[6:7], v[6:7], v[104:105] op_sel_hi:[1,0]
	v_pk_mul_f32 v[4:5], v[4:5], v[104:105] op_sel_hi:[1,0]
	v_pk_mul_f32 v[2:3], v[2:3], v[104:105] op_sel_hi:[1,0]
	v_mul_f32_e32 v93, v93, v104
.LBB0_389:
	s_waitcnt lgkmcnt(1)
	v_mfma_f32_32x32x16_bf16 v[34:49], v[182:185], v[76:79], v[34:49]
	v_add_f32_e32 v148, v103, v146
	ds_read2_b64 v[122:125], v101 offset1:2
	ds_read2_b64 v[126:129], v100 offset1:2
	ds_read2_b64 v[130:133], v101 offset0:4 offset1:6
	ds_read2_b64 v[134:137], v100 offset0:4 offset1:6
	v_pk_add_f32 v[50:51], v[50:51], v[148:149] op_sel_hi:[1,0] neg_lo:[0,1] neg_hi:[0,1]
	v_pk_add_f32 v[52:53], v[52:53], v[148:149] op_sel_hi:[1,0] neg_lo:[0,1] neg_hi:[0,1]
	v_exp_f32_e32 v50, v50
	v_pk_add_f32 v[54:55], v[54:55], v[148:149] op_sel_hi:[1,0] neg_lo:[0,1] neg_hi:[0,1]
	v_exp_f32_e32 v51, v51
	v_pk_add_f32 v[56:57], v[56:57], v[148:149] op_sel_hi:[1,0] neg_lo:[0,1] neg_hi:[0,1]
	v_exp_f32_e32 v52, v52
	s_waitcnt lgkmcnt(4)
	v_mfma_f32_32x32x16_bf16 v[220:235], v[186:189], v[80:83], v[220:235]
	v_pk_add_f32 v[58:59], v[58:59], v[148:149] op_sel_hi:[1,0] neg_lo:[0,1] neg_hi:[0,1]
	v_exp_f32_e32 v53, v53
	v_pk_add_f32 v[60:61], v[60:61], v[148:149] op_sel_hi:[1,0] neg_lo:[0,1] neg_hi:[0,1]
	v_exp_f32_e32 v54, v54
	v_pk_add_f32 v[62:63], v[62:63], v[148:149] op_sel_hi:[1,0] neg_lo:[0,1] neg_hi:[0,1]
	v_exp_f32_e32 v55, v55
	v_pk_add_f32 v[64:65], v[64:65], v[148:149] op_sel_hi:[1,0] neg_lo:[0,1] neg_hi:[0,1]
	v_exp_f32_e32 v56, v56
	v_cvt_pk_bf16_f32 v150, v50, v51
	v_exp_f32_e32 v57, v57
	v_cvt_pk_bf16_f32 v151, v52, v53
	v_exp_f32_e32 v58, v58
	v_pk_add_f32 v[236:237], v[50:51], v[52:53]
	v_exp_f32_e32 v59, v59
	v_cvt_pk_bf16_f32 v152, v54, v55
	v_exp_f32_e32 v60, v60
	v_pk_add_f32 v[236:237], v[236:237], v[54:55]
	v_exp_f32_e32 v61, v61
	v_cvt_pk_bf16_f32 v153, v56, v57
	v_exp_f32_e32 v62, v62
	v_pk_add_f32 v[236:237], v[236:237], v[56:57]
	v_exp_f32_e32 v63, v63
	s_add_i32 s24, s24, 1
	s_sub_i32 s23, s23, 32
	s_waitcnt lgkmcnt(3)
	v_mfma_f32_32x32x16_bf16 v[18:33], v[122:125], v[150:153], v[18:33]
	v_exp_f32_e32 v64, v64
	v_cvt_pk_bf16_f32 v140, v58, v59
	v_exp_f32_e32 v65, v65
	v_cvt_pk_bf16_f32 v141, v60, v61
	v_pk_add_f32 v[236:237], v[236:237], v[58:59]
	s_waitcnt lgkmcnt(2)
	v_mfma_f32_32x32x16_bf16 v[2:17], v[126:129], v[150:153], v[2:17]
	v_cvt_pk_bf16_f32 v142, v62, v63
	v_pk_add_f32 v[236:237], v[236:237], v[60:61]
	v_cvt_pk_bf16_f32 v143, v64, v65
	v_pk_add_f32 v[236:237], v[236:237], v[62:63]
	v_pk_add_f32 v[236:237], v[236:237], v[64:65]
	v_add_u32_e32 v100, 64, v100
	s_waitcnt lgkmcnt(1)
	v_mfma_f32_32x32x16_bf16 v[18:33], v[130:133], v[140:143], v[18:33]
	v_add_u32_e32 v101, 64, v101
	v_add_f32_e32 v236, v236, v237
	s_waitcnt lgkmcnt(0)
	v_mfma_f32_32x32x16_bf16 v[2:17], v[134:137], v[140:143], v[2:17]
	v_add_f32_e32 v93, v93, v236
	s_cmpk_eq_i32 s23, 0xfee0
	v_add_u32_e32 v92, 0x1200, v92
	s_cbranch_scc1 .LBB0_379
	v_pk_add_f32 v[64:65], v[48:49], v[234:235]
	v_pk_add_f32 v[62:63], v[46:47], v[232:233]
	v_pk_add_f32 v[60:61], v[44:45], v[230:231]
	v_pk_add_f32 v[58:59], v[42:43], v[228:229]
	v_pk_add_f32 v[56:57], v[40:41], v[226:227]
	v_pk_add_f32 v[54:55], v[38:39], v[224:225]
	v_pk_add_f32 v[52:53], v[36:37], v[222:223]
	v_pk_add_f32 v[50:51], v[34:35], v[220:221]
	s_branch .LBB0_381
